# attention max chains split/overlapped with MFMA latency; scan inner-loop DPP gaps filled with LDS reads
# speedup vs baseline: 1.0436x; 1.0080x over previous
; template <int CTRL> DI float dppf(float v) { return __int_as_float(__builtin_amdgcn_update_dpp(0, __float_as_int(v), CTRL, 0xf, 0xf, false)); }
; DI float red16(float p) { p += dppf<0xB1>(p); p += dppf<0x4E>(p); p += dppf<0x141>(p); p += dppf<0x140>(p); return p; }
; DI void scan_task(const Params& P, int sb, unsigned char* lds) {
;     ...
;         for (int i = 0; i < 4; ++i) {
;           ld_ops(nx3, gb + (i + 3) * SREC, q4);
;           const f2 a01 = {cur.a.x, cur.a.y}, a23 = {cur.a.z, cur.a.w}, w01 = {cur.w.x, cur.w.y}, w23 = {cur.w.z, cur.w.w};
;           const f2 k01 = {cur.k.x, cur.k.y}, k23 = {cur.k.z, cur.k.w}, b01 = {cur.b.x, cur.b.y}, b23 = {cur.b.z, cur.b.w};
;           const f2 r01 = {cur.r.x, cur.r.y}, r23 = {cur.r.z, cur.r.w};
;           f2 pa = S0 * a01; pa += S1 * a23;
;           const float vs = (i == 0) ? v4.x : (i == 1) ? v4.y : (i == 2) ? v4.z : v4.w;
;           const f2 vv = {vs, vs};
;           const f2 t0 = S0 * w01 + vv * k01, t1 = S1 * w23 + vv * k23;
;           const float sa = red16(pa.x + pa.y);
;           const f2 sa2 = {sa, sa};
;           S0 = t0 + sa2 * b01; S1 = t1 + sa2 * b23;
;           f2 py = S0 * r01; py += S1 * r23;
;           pp[i] = py.x + py.y;
;           cur = nxt; nxt = nx2; nx2 = nx3;
;         }
;         const float tA = o1 ? pp[0] : pp[1], kA = o1 ? pp[1] : pp[0];
;         const float tB = o1 ? pp[2] : pp[3], kB = o1 ? pp[3] : pp[2];
;         const float r0 = kA + dppf<0xB1>(tA), r1 = kB + dppf<0xB1>(tB);
;         const float tC = o2 ? r0 : r1, kC = o2 ? r1 : r0;
;         float u = kC + dppf<0x4E>(tC);
;         u += dppf<0x124>(u);
;         u += dppf<0x128>(u);
;         yb[(g4 * 4 + (q & 3)) * 16 + rowl] = u;
.LBB0_1198:
	v_add_u32_e32 v100, 0x18000, v74
	s_waitcnt lgkmcnt(14)
	v_pk_mul_f32 v[2:3], v[64:65], v[2:3]
	ds_read_b128 v[60:63], v72 offset:256
	ds_read_b128 v[76:79], v72 offset:512
	ds_read_b128 v[80:83], v72 offset:768
	ds_read_b128 v[84:87], v72 offset:1024
	ds_read_b128 v[88:91], v100
	ds_read_b128 v[92:95], v72
	v_pk_fma_f32 v[96:97], v[66:67], v[0:1], v[2:3]
	ds_read_b128 v[0:3], v72 offset:1408
	v_add_f32_e32 v75, v96, v97
	s_waitcnt lgkmcnt(2)
	v_pk_mul_f32 v[14:15], v[14:15], v[88:89] op_sel_hi:[1,0]
	v_pk_mul_f32 v[12:13], v[12:13], v[88:89] op_sel_hi:[1,0]
	v_add_f32_dpp v75, v75, v75 quad_perm:[1,0,3,2] row_mask:0xf bank_mask:0xf bound_ctrl:1
	v_pk_fma_f32 v[64:65], v[64:65], v[10:11], v[14:15]
	v_pk_fma_f32 v[66:67], v[66:67], v[8:9], v[12:13]
	v_add_f32_dpp v75, v75, v75 quad_perm:[2,3,0,1] row_mask:0xf bank_mask:0xf bound_ctrl:1
	v_mov_b32_e32 v98, v91
	ds_read_b128 v[8:11], v72 offset:1920
	ds_read_b128 v[12:15], v72 offset:2176
	v_add_f32_dpp v75, v75, v75 row_half_mirror row_mask:0xf bank_mask:0xf bound_ctrl:1
	s_nop 1
	v_add_f32_dpp v96, v75, v75 row_mirror row_mask:0xf bank_mask:0xf bound_ctrl:1
	v_pk_fma_f32 v[64:65], v[6:7], v[96:97], v[64:65] op_sel_hi:[1,0,1]
	v_pk_fma_f32 v[66:67], v[4:5], v[96:97], v[66:67] op_sel_hi:[1,0,1]
	v_pk_mul_f32 v[18:19], v[18:19], v[64:65]
	v_pk_mul_f32 v[22:23], v[22:23], v[64:65]
	v_pk_mul_f32 v[36:37], v[36:37], v[66:67]
	v_pk_mul_f32 v[38:39], v[38:39], v[64:65]
	v_pk_fma_f32 v[64:65], v[16:17], v[66:67], v[18:19]
	v_pk_fma_f32 v[66:67], v[20:21], v[66:67], v[22:23]
	v_add_f32_e32 v75, v64, v65
	v_add_f32_e32 v64, v66, v67
	v_pk_fma_f32 v[36:37], v[28:29], v[88:89], v[36:37] op_sel:[0,1,0]
	v_pk_fma_f32 v[38:39], v[30:31], v[88:89], v[38:39] op_sel:[0,1,0]
	v_add_f32_dpp v64, v64, v64 quad_perm:[1,0,3,2] row_mask:0xf bank_mask:0xf bound_ctrl:1
	ds_read_b128 v[4:7], v72 offset:1664
	ds_read_b128 v[16:19], v72 offset:2432
	v_add_f32_dpp v64, v64, v64 quad_perm:[2,3,0,1] row_mask:0xf bank_mask:0xf bound_ctrl:1
	ds_read_b128 v[20:23], v72 offset:2816
	ds_read_b128 v[28:31], v72 offset:3584
	v_add_f32_dpp v64, v64, v64 row_half_mirror row_mask:0xf bank_mask:0xf bound_ctrl:1
	s_nop 1
	v_add_f32_dpp v64, v64, v64 row_mirror row_mask:0xf bank_mask:0xf bound_ctrl:1
	v_pk_fma_f32 v[66:67], v[24:25], v[64:65], v[36:37] op_sel_hi:[1,0,1]
	v_pk_fma_f32 v[64:65], v[26:27], v[64:65], v[38:39] op_sel_hi:[1,0,1]
	v_pk_mul_f32 v[88:89], v[48:49], v[66:67]
	v_pk_mul_f32 v[34:35], v[34:35], v[64:65]
	v_pk_mul_f32 v[42:43], v[42:43], v[64:65]
	v_pk_fma_f32 v[96:97], v[32:33], v[66:67], v[34:35]
	v_pk_fma_f32 v[66:67], v[40:41], v[66:67], v[42:43]
	v_pk_mul_f32 v[64:65], v[50:51], v[64:65]
	v_add_f32_e32 v66, v66, v67
	v_pk_fma_f32 v[88:89], v[52:53], v[90:91], v[88:89] op_sel_hi:[1,0,1]
	v_pk_fma_f32 v[64:65], v[54:55], v[90:91], v[64:65] op_sel_hi:[1,0,1]
	v_add_f32_dpp v66, v66, v66 quad_perm:[1,0,3,2] row_mask:0xf bank_mask:0xf bound_ctrl:1
	v_add_f32_e32 v90, v96, v97
	v_cndmask_b32_e32 v67, v75, v90, vcc
	v_add_f32_dpp v66, v66, v66 quad_perm:[2,3,0,1] row_mask:0xf bank_mask:0xf bound_ctrl:1
	v_cndmask_b32_e32 v75, v90, v75, vcc
	ds_read_b128 v[24:27], v72 offset:3072
	ds_read_b128 v[36:39], v72 offset:3328
	v_add_f32_dpp v66, v66, v66 row_half_mirror row_mask:0xf bank_mask:0xf bound_ctrl:1
	v_add_f32_dpp v105, v67, v75 quad_perm:[1,0,3,2] row_mask:0xf bank_mask:0xf bound_ctrl:1
	ds_read_b128 v[48:51], v72 offset:4736
	ds_read_b128 v[32:35], v72 offset:3840
	v_add_f32_dpp v66, v66, v66 row_mirror row_mask:0xf bank_mask:0xf bound_ctrl:1
	v_pk_fma_f32 v[64:65], v[46:47], v[66:67], v[64:65] op_sel_hi:[1,0,1]
	v_pk_fma_f32 v[88:89], v[44:45], v[66:67], v[88:89] op_sel_hi:[1,0,1]
	s_waitcnt lgkmcnt(11)
	v_pk_mul_f32 v[66:67], v[94:95], v[64:65]
	v_pk_mul_f32 v[58:59], v[58:59], v[64:65]
	v_pk_fma_f32 v[66:67], v[92:93], v[88:89], v[66:67]
	v_pk_mul_f32 v[64:65], v[78:79], v[64:65]
	v_add_f32_e32 v66, v66, v67
	v_pk_fma_f32 v[78:79], v[56:57], v[88:89], v[58:59]
	v_pk_mul_f32 v[76:77], v[76:77], v[88:89]
	v_add_f32_dpp v66, v66, v66 quad_perm:[1,0,3,2] row_mask:0xf bank_mask:0xf bound_ctrl:1
	v_pk_fma_f32 v[64:65], v[98:99], v[82:83], v[64:65] op_sel_hi:[0,1,1]
	v_add_f32_e32 v104, v78, v79
	v_add_f32_dpp v66, v66, v66 quad_perm:[2,3,0,1] row_mask:0xf bank_mask:0xf bound_ctrl:1
	v_pk_fma_f32 v[76:77], v[98:99], v[80:81], v[76:77] op_sel_hi:[0,1,1]
	ds_read_b128 v[40:43], v72 offset:4224
	ds_read_b128 v[52:55], v72 offset:4992
	v_add_f32_dpp v66, v66, v66 row_half_mirror row_mask:0xf bank_mask:0xf bound_ctrl:1
	ds_read_b128 v[44:47], v72 offset:4480
	ds_read_b128 v[56:59], v72 offset:5248
	v_add_f32_dpp v78, v66, v66 row_mirror row_mask:0xf bank_mask:0xf bound_ctrl:1
	v_pk_fma_f32 v[64:65], v[62:63], v[78:79], v[64:65] op_sel_hi:[1,0,1]
	v_pk_fma_f32 v[66:67], v[60:61], v[78:79], v[76:77] op_sel_hi:[1,0,1]
	v_pk_mul_f32 v[102:103], v[86:87], v[64:65]
	v_pk_fma_f32 v[102:103], v[84:85], v[66:67], v[102:103]
	s_waitcnt lgkmcnt(14)
	v_pk_mul_f32 v[2:3], v[64:65], v[2:3]
	v_add_f32_e32 v102, v102, v103
	ds_read_b128 v[60:63], v72 offset:5888
	v_cndmask_b32_e32 v106, v104, v102, vcc
	v_cndmask_b32_e32 v102, v102, v104, vcc
	ds_read_b128 v[76:79], v72 offset:6144
	ds_read_b128 v[80:83], v72 offset:6400
	ds_read_b128 v[84:87], v72 offset:6656
	ds_read_b128 v[88:91], v100 offset:16
	ds_read_b128 v[92:95], v72 offset:5632
	v_add_f32_dpp v102, v106, v102 quad_perm:[1,0,3,2] row_mask:0xf bank_mask:0xf bound_ctrl:1
	v_pk_fma_f32 v[96:97], v[66:67], v[0:1], v[2:3]
	v_cndmask_b32_e64 v106, v105, v102, s[4:5]
	v_cndmask_b32_e64 v102, v102, v105, s[4:5]
	ds_read_b128 v[0:3], v72 offset:7040
	v_add_f32_e32 v75, v96, v97
	s_waitcnt lgkmcnt(2)
; template <int CTRL> DI float dppf(float v) { return __int_as_float(__builtin_amdgcn_update_dpp(0, __float_as_int(v), CTRL, 0xf, 0xf, false)); }
; DI float red16(float p) { p += dppf<0xB1>(p); p += dppf<0x4E>(p); p += dppf<0x141>(p); p += dppf<0x140>(p); return p; }
; DI void scan_task(const Params& P, int sb, unsigned char* lds) {
;     ...
;         for (int i = 0; i < 4; ++i) {
;           ld_ops(nx3, gb + (i + 3) * SREC, q4);
;           const f2 a01 = {cur.a.x, cur.a.y}, a23 = {cur.a.z, cur.a.w}, w01 = {cur.w.x, cur.w.y}, w23 = {cur.w.z, cur.w.w};
;           const f2 k01 = {cur.k.x, cur.k.y}, k23 = {cur.k.z, cur.k.w}, b01 = {cur.b.x, cur.b.y}, b23 = {cur.b.z, cur.b.w};
;           const f2 r01 = {cur.r.x, cur.r.y}, r23 = {cur.r.z, cur.r.w};
;           f2 pa = S0 * a01; pa += S1 * a23;
;           const float vs = (i == 0) ? v4.x : (i == 1) ? v4.y : (i == 2) ? v4.z : v4.w;
;           const f2 vv = {vs, vs};
;           const f2 t0 = S0 * w01 + vv * k01, t1 = S1 * w23 + vv * k23;
;           const float sa = red16(pa.x + pa.y);
;           const f2 sa2 = {sa, sa};
;           S0 = t0 + sa2 * b01; S1 = t1 + sa2 * b23;
;           f2 py = S0 * r01; py += S1 * r23;
;           pp[i] = py.x + py.y;
;           cur = nxt; nxt = nx2; nx2 = nx3;
;         }
;         const float tA = o1 ? pp[0] : pp[1], kA = o1 ? pp[1] : pp[0];
;         const float tB = o1 ? pp[2] : pp[3], kB = o1 ? pp[3] : pp[2];
;         const float r0 = kA + dppf<0xB1>(tA), r1 = kB + dppf<0xB1>(tB);
;         const float tC = o2 ? r0 : r1, kC = o2 ? r1 : r0;
;         float u = kC + dppf<0x4E>(tC);
;         u += dppf<0x124>(u);
;         u += dppf<0x128>(u);
;         yb[(g4 * 4 + (q & 3)) * 16 + rowl] = u;
	v_add_f32_dpp v102, v106, v102 quad_perm:[2,3,0,1] row_mask:0xf bank_mask:0xf bound_ctrl:1
	v_pk_mul_f32 v[14:15], v[14:15], v[88:89] op_sel_hi:[1,0]
	v_pk_mul_f32 v[12:13], v[12:13], v[88:89] op_sel_hi:[1,0]
	v_add_f32_dpp v102, v102, v102 row_ror:4 row_mask:0xf bank_mask:0xf bound_ctrl:1
	v_add_f32_dpp v75, v75, v75 quad_perm:[1,0,3,2] row_mask:0xf bank_mask:0xf bound_ctrl:1
	v_pk_fma_f32 v[64:65], v[64:65], v[10:11], v[14:15]
	v_pk_fma_f32 v[66:67], v[66:67], v[8:9], v[12:13]
	v_add_f32_dpp v102, v102, v102 row_ror:8 row_mask:0xf bank_mask:0xf bound_ctrl:1
	v_add_f32_dpp v75, v75, v75 quad_perm:[2,3,0,1] row_mask:0xf bank_mask:0xf bound_ctrl:1
	v_mov_b32_e32 v98, v91
	ds_write_b32 v73, v102
	v_add_f32_dpp v75, v75, v75 row_half_mirror row_mask:0xf bank_mask:0xf bound_ctrl:1
	ds_read_b128 v[8:11], v72 offset:7552
	ds_read_b128 v[12:15], v72 offset:7808
	v_add_f32_dpp v96, v75, v75 row_mirror row_mask:0xf bank_mask:0xf bound_ctrl:1
	v_pk_fma_f32 v[64:65], v[6:7], v[96:97], v[64:65] op_sel_hi:[1,0,1]
	v_pk_fma_f32 v[66:67], v[4:5], v[96:97], v[66:67] op_sel_hi:[1,0,1]
	v_pk_mul_f32 v[18:19], v[18:19], v[64:65]
	v_pk_mul_f32 v[22:23], v[22:23], v[64:65]
	v_pk_mul_f32 v[36:37], v[36:37], v[66:67]
	v_pk_mul_f32 v[38:39], v[38:39], v[64:65]
	v_pk_fma_f32 v[64:65], v[16:17], v[66:67], v[18:19]
	v_pk_fma_f32 v[66:67], v[20:21], v[66:67], v[22:23]
	v_add_f32_e32 v75, v64, v65
	v_add_f32_e32 v64, v66, v67
	v_pk_fma_f32 v[36:37], v[28:29], v[88:89], v[36:37] op_sel:[0,1,0]
	v_pk_fma_f32 v[38:39], v[30:31], v[88:89], v[38:39] op_sel:[0,1,0]
	v_add_f32_dpp v64, v64, v64 quad_perm:[1,0,3,2] row_mask:0xf bank_mask:0xf bound_ctrl:1
	ds_read_b128 v[4:7], v72 offset:7296
	ds_read_b128 v[16:19], v72 offset:8064
	v_add_f32_dpp v64, v64, v64 quad_perm:[2,3,0,1] row_mask:0xf bank_mask:0xf bound_ctrl:1
	ds_read_b128 v[20:23], v72 offset:8448
	ds_read_b128 v[28:31], v72 offset:9216
	v_add_f32_dpp v64, v64, v64 row_half_mirror row_mask:0xf bank_mask:0xf bound_ctrl:1
	s_nop 1
	v_add_f32_dpp v64, v64, v64 row_mirror row_mask:0xf bank_mask:0xf bound_ctrl:1
	v_pk_fma_f32 v[66:67], v[24:25], v[64:65], v[36:37] op_sel_hi:[1,0,1]
	v_pk_fma_f32 v[64:65], v[26:27], v[64:65], v[38:39] op_sel_hi:[1,0,1]
	v_pk_mul_f32 v[88:89], v[48:49], v[66:67]
	v_pk_mul_f32 v[34:35], v[34:35], v[64:65]
	v_pk_mul_f32 v[42:43], v[42:43], v[64:65]
	v_pk_fma_f32 v[96:97], v[32:33], v[66:67], v[34:35]
	v_pk_fma_f32 v[66:67], v[40:41], v[66:67], v[42:43]
	v_pk_mul_f32 v[64:65], v[50:51], v[64:65]
	v_add_f32_e32 v66, v66, v67
	v_pk_fma_f32 v[88:89], v[52:53], v[90:91], v[88:89] op_sel_hi:[1,0,1]
	v_pk_fma_f32 v[64:65], v[54:55], v[90:91], v[64:65] op_sel_hi:[1,0,1]
	v_add_f32_dpp v66, v66, v66 quad_perm:[1,0,3,2] row_mask:0xf bank_mask:0xf bound_ctrl:1
	v_add_f32_e32 v90, v96, v97
	v_cndmask_b32_e32 v67, v75, v90, vcc
	v_add_f32_dpp v66, v66, v66 quad_perm:[2,3,0,1] row_mask:0xf bank_mask:0xf bound_ctrl:1
	v_cndmask_b32_e32 v75, v90, v75, vcc
	ds_read_b128 v[24:27], v72 offset:8704
	ds_read_b128 v[36:39], v72 offset:8960
	v_add_f32_dpp v66, v66, v66 row_half_mirror row_mask:0xf bank_mask:0xf bound_ctrl:1
	v_add_f32_dpp v105, v67, v75 quad_perm:[1,0,3,2] row_mask:0xf bank_mask:0xf bound_ctrl:1
	ds_read_b128 v[48:51], v72 offset:10368
	ds_read_b128 v[32:35], v72 offset:9472
	v_add_f32_dpp v66, v66, v66 row_mirror row_mask:0xf bank_mask:0xf bound_ctrl:1
	v_pk_fma_f32 v[64:65], v[46:47], v[66:67], v[64:65] op_sel_hi:[1,0,1]
	v_pk_fma_f32 v[88:89], v[44:45], v[66:67], v[88:89] op_sel_hi:[1,0,1]
	s_waitcnt lgkmcnt(11)
	v_pk_mul_f32 v[66:67], v[94:95], v[64:65]
	v_pk_mul_f32 v[58:59], v[58:59], v[64:65]
	v_pk_fma_f32 v[66:67], v[92:93], v[88:89], v[66:67]
	v_pk_mul_f32 v[64:65], v[78:79], v[64:65]
	v_add_f32_e32 v66, v66, v67
	v_pk_fma_f32 v[78:79], v[56:57], v[88:89], v[58:59]
	v_pk_mul_f32 v[76:77], v[76:77], v[88:89]
	v_add_f32_dpp v66, v66, v66 quad_perm:[1,0,3,2] row_mask:0xf bank_mask:0xf bound_ctrl:1
	v_pk_fma_f32 v[64:65], v[98:99], v[82:83], v[64:65] op_sel_hi:[0,1,1]
	v_add_f32_e32 v104, v78, v79
	v_add_f32_dpp v66, v66, v66 quad_perm:[2,3,0,1] row_mask:0xf bank_mask:0xf bound_ctrl:1
	v_pk_fma_f32 v[76:77], v[98:99], v[80:81], v[76:77] op_sel_hi:[0,1,1]
	ds_read_b128 v[40:43], v72 offset:9856
	ds_read_b128 v[52:55], v72 offset:10624
	v_add_f32_dpp v66, v66, v66 row_half_mirror row_mask:0xf bank_mask:0xf bound_ctrl:1
	ds_read_b128 v[44:47], v72 offset:10112
	ds_read_b128 v[56:59], v72 offset:10880
	v_add_f32_dpp v78, v66, v66 row_mirror row_mask:0xf bank_mask:0xf bound_ctrl:1
	v_pk_fma_f32 v[64:65], v[62:63], v[78:79], v[64:65] op_sel_hi:[1,0,1]
	v_pk_fma_f32 v[66:67], v[60:61], v[78:79], v[76:77] op_sel_hi:[1,0,1]
	v_pk_mul_f32 v[102:103], v[86:87], v[64:65]
	v_pk_fma_f32 v[102:103], v[84:85], v[66:67], v[102:103]
	s_waitcnt lgkmcnt(14)
	v_pk_mul_f32 v[2:3], v[64:65], v[2:3]
	v_add_f32_e32 v102, v102, v103
	ds_read_b128 v[60:63], v72 offset:11520
	v_cndmask_b32_e32 v106, v104, v102, vcc
	v_cndmask_b32_e32 v102, v102, v104, vcc
	ds_read_b128 v[76:79], v72 offset:11776
	ds_read_b128 v[80:83], v72 offset:12032
	ds_read_b128 v[84:87], v72 offset:12288
	ds_read_b128 v[88:91], v100 offset:32
	ds_read_b128 v[92:95], v72 offset:11264
	v_add_f32_dpp v102, v106, v102 quad_perm:[1,0,3,2] row_mask:0xf bank_mask:0xf bound_ctrl:1
	v_pk_fma_f32 v[96:97], v[66:67], v[0:1], v[2:3]
	v_cndmask_b32_e64 v106, v105, v102, s[4:5]
	v_cndmask_b32_e64 v102, v102, v105, s[4:5]
	ds_read_b128 v[0:3], v72 offset:12672
	v_add_f32_e32 v75, v96, v97
	s_waitcnt lgkmcnt(2)
; template <int CTRL> DI float dppf(float v) { return __int_as_float(__builtin_amdgcn_update_dpp(0, __float_as_int(v), CTRL, 0xf, 0xf, false)); }
; DI float red16(float p) { p += dppf<0xB1>(p); p += dppf<0x4E>(p); p += dppf<0x141>(p); p += dppf<0x140>(p); return p; }
; DI void scan_task(const Params& P, int sb, unsigned char* lds) {
;     ...
;         for (int i = 0; i < 4; ++i) {
;           ld_ops(nx3, gb + (i + 3) * SREC, q4);
;           const f2 a01 = {cur.a.x, cur.a.y}, a23 = {cur.a.z, cur.a.w}, w01 = {cur.w.x, cur.w.y}, w23 = {cur.w.z, cur.w.w};
;           const f2 k01 = {cur.k.x, cur.k.y}, k23 = {cur.k.z, cur.k.w}, b01 = {cur.b.x, cur.b.y}, b23 = {cur.b.z, cur.b.w};
;           const f2 r01 = {cur.r.x, cur.r.y}, r23 = {cur.r.z, cur.r.w};
;           f2 pa = S0 * a01; pa += S1 * a23;
;           const float vs = (i == 0) ? v4.x : (i == 1) ? v4.y : (i == 2) ? v4.z : v4.w;
;           const f2 vv = {vs, vs};
;           const f2 t0 = S0 * w01 + vv * k01, t1 = S1 * w23 + vv * k23;
;           const float sa = red16(pa.x + pa.y);
;           const f2 sa2 = {sa, sa};
;           S0 = t0 + sa2 * b01; S1 = t1 + sa2 * b23;
;           f2 py = S0 * r01; py += S1 * r23;
;           pp[i] = py.x + py.y;
;           cur = nxt; nxt = nx2; nx2 = nx3;
;         }
;         const float tA = o1 ? pp[0] : pp[1], kA = o1 ? pp[1] : pp[0];
;         const float tB = o1 ? pp[2] : pp[3], kB = o1 ? pp[3] : pp[2];
;         const float r0 = kA + dppf<0xB1>(tA), r1 = kB + dppf<0xB1>(tB);
;         const float tC = o2 ? r0 : r1, kC = o2 ? r1 : r0;
;         float u = kC + dppf<0x4E>(tC);
;         u += dppf<0x124>(u);
;         u += dppf<0x128>(u);
;         yb[(g4 * 4 + (q & 3)) * 16 + rowl] = u;
	v_add_f32_dpp v102, v106, v102 quad_perm:[2,3,0,1] row_mask:0xf bank_mask:0xf bound_ctrl:1
	v_pk_mul_f32 v[14:15], v[14:15], v[88:89] op_sel_hi:[1,0]
	v_pk_mul_f32 v[12:13], v[12:13], v[88:89] op_sel_hi:[1,0]
	v_add_f32_dpp v102, v102, v102 row_ror:4 row_mask:0xf bank_mask:0xf bound_ctrl:1
	v_add_f32_dpp v75, v75, v75 quad_perm:[1,0,3,2] row_mask:0xf bank_mask:0xf bound_ctrl:1
	v_pk_fma_f32 v[64:65], v[64:65], v[10:11], v[14:15]
	v_pk_fma_f32 v[66:67], v[66:67], v[8:9], v[12:13]
	v_add_f32_dpp v102, v102, v102 row_ror:8 row_mask:0xf bank_mask:0xf bound_ctrl:1
	v_add_f32_dpp v75, v75, v75 quad_perm:[2,3,0,1] row_mask:0xf bank_mask:0xf bound_ctrl:1
	v_mov_b32_e32 v98, v91
	ds_write_b32 v73, v102 offset:256
	v_add_f32_dpp v75, v75, v75 row_half_mirror row_mask:0xf bank_mask:0xf bound_ctrl:1
	ds_read_b128 v[8:11], v72 offset:13184
	ds_read_b128 v[12:15], v72 offset:13440
	v_add_f32_dpp v96, v75, v75 row_mirror row_mask:0xf bank_mask:0xf bound_ctrl:1
	v_pk_fma_f32 v[64:65], v[6:7], v[96:97], v[64:65] op_sel_hi:[1,0,1]
	v_pk_fma_f32 v[66:67], v[4:5], v[96:97], v[66:67] op_sel_hi:[1,0,1]
	v_pk_mul_f32 v[18:19], v[18:19], v[64:65]
	v_pk_mul_f32 v[22:23], v[22:23], v[64:65]
	v_pk_mul_f32 v[36:37], v[36:37], v[66:67]
	v_pk_mul_f32 v[38:39], v[38:39], v[64:65]
	v_pk_fma_f32 v[64:65], v[16:17], v[66:67], v[18:19]
	v_pk_fma_f32 v[66:67], v[20:21], v[66:67], v[22:23]
	v_add_f32_e32 v75, v64, v65
	v_add_f32_e32 v64, v66, v67
	v_pk_fma_f32 v[36:37], v[28:29], v[88:89], v[36:37] op_sel:[0,1,0]
	v_pk_fma_f32 v[38:39], v[30:31], v[88:89], v[38:39] op_sel:[0,1,0]
	v_add_f32_dpp v64, v64, v64 quad_perm:[1,0,3,2] row_mask:0xf bank_mask:0xf bound_ctrl:1
	ds_read_b128 v[4:7], v72 offset:12928
	ds_read_b128 v[16:19], v72 offset:13696
	v_add_f32_dpp v64, v64, v64 quad_perm:[2,3,0,1] row_mask:0xf bank_mask:0xf bound_ctrl:1
	ds_read_b128 v[20:23], v72 offset:14080
	ds_read_b128 v[28:31], v72 offset:14848
	v_add_f32_dpp v64, v64, v64 row_half_mirror row_mask:0xf bank_mask:0xf bound_ctrl:1
	s_nop 1
	v_add_f32_dpp v64, v64, v64 row_mirror row_mask:0xf bank_mask:0xf bound_ctrl:1
	v_pk_fma_f32 v[66:67], v[24:25], v[64:65], v[36:37] op_sel_hi:[1,0,1]
	v_pk_fma_f32 v[64:65], v[26:27], v[64:65], v[38:39] op_sel_hi:[1,0,1]
	v_pk_mul_f32 v[88:89], v[48:49], v[66:67]
	v_pk_mul_f32 v[34:35], v[34:35], v[64:65]
	v_pk_mul_f32 v[42:43], v[42:43], v[64:65]
	v_pk_fma_f32 v[96:97], v[32:33], v[66:67], v[34:35]
	v_pk_fma_f32 v[66:67], v[40:41], v[66:67], v[42:43]
	v_pk_mul_f32 v[64:65], v[50:51], v[64:65]
	v_add_f32_e32 v66, v66, v67
	v_pk_fma_f32 v[88:89], v[52:53], v[90:91], v[88:89] op_sel_hi:[1,0,1]
	v_pk_fma_f32 v[64:65], v[54:55], v[90:91], v[64:65] op_sel_hi:[1,0,1]
	v_add_f32_dpp v66, v66, v66 quad_perm:[1,0,3,2] row_mask:0xf bank_mask:0xf bound_ctrl:1
	v_add_f32_e32 v90, v96, v97
	v_cndmask_b32_e32 v67, v75, v90, vcc
	v_add_f32_dpp v66, v66, v66 quad_perm:[2,3,0,1] row_mask:0xf bank_mask:0xf bound_ctrl:1
	v_cndmask_b32_e32 v75, v90, v75, vcc
	ds_read_b128 v[24:27], v72 offset:14336
	ds_read_b128 v[36:39], v72 offset:14592
	v_add_f32_dpp v66, v66, v66 row_half_mirror row_mask:0xf bank_mask:0xf bound_ctrl:1
	v_add_f32_dpp v105, v67, v75 quad_perm:[1,0,3,2] row_mask:0xf bank_mask:0xf bound_ctrl:1
	ds_read_b128 v[48:51], v72 offset:16000
	ds_read_b128 v[32:35], v72 offset:15104
	v_add_f32_dpp v66, v66, v66 row_mirror row_mask:0xf bank_mask:0xf bound_ctrl:1
	v_pk_fma_f32 v[64:65], v[46:47], v[66:67], v[64:65] op_sel_hi:[1,0,1]
	v_pk_fma_f32 v[88:89], v[44:45], v[66:67], v[88:89] op_sel_hi:[1,0,1]
	s_waitcnt lgkmcnt(11)
	v_pk_mul_f32 v[66:67], v[94:95], v[64:65]
	v_pk_mul_f32 v[58:59], v[58:59], v[64:65]
	v_pk_fma_f32 v[66:67], v[92:93], v[88:89], v[66:67]
	v_pk_mul_f32 v[64:65], v[78:79], v[64:65]
	v_add_f32_e32 v66, v66, v67
	v_pk_fma_f32 v[78:79], v[56:57], v[88:89], v[58:59]
	v_pk_mul_f32 v[76:77], v[76:77], v[88:89]
	v_add_f32_dpp v66, v66, v66 quad_perm:[1,0,3,2] row_mask:0xf bank_mask:0xf bound_ctrl:1
	v_pk_fma_f32 v[64:65], v[98:99], v[82:83], v[64:65] op_sel_hi:[0,1,1]
	v_add_f32_e32 v104, v78, v79
	v_add_f32_dpp v66, v66, v66 quad_perm:[2,3,0,1] row_mask:0xf bank_mask:0xf bound_ctrl:1
	v_pk_fma_f32 v[76:77], v[98:99], v[80:81], v[76:77] op_sel_hi:[0,1,1]
	ds_read_b128 v[40:43], v72 offset:15488
	ds_read_b128 v[52:55], v72 offset:16256
	v_add_f32_dpp v66, v66, v66 row_half_mirror row_mask:0xf bank_mask:0xf bound_ctrl:1
	ds_read_b128 v[44:47], v72 offset:15744
	ds_read_b128 v[56:59], v72 offset:16512
	v_add_f32_dpp v78, v66, v66 row_mirror row_mask:0xf bank_mask:0xf bound_ctrl:1
	v_pk_fma_f32 v[64:65], v[62:63], v[78:79], v[64:65] op_sel_hi:[1,0,1]
	v_pk_fma_f32 v[66:67], v[60:61], v[78:79], v[76:77] op_sel_hi:[1,0,1]
	v_pk_mul_f32 v[102:103], v[86:87], v[64:65]
	v_pk_fma_f32 v[102:103], v[84:85], v[66:67], v[102:103]
	s_waitcnt lgkmcnt(14)
	v_pk_mul_f32 v[2:3], v[64:65], v[2:3]
	v_add_f32_e32 v102, v102, v103
	ds_read_b128 v[60:63], v72 offset:17152
	v_cndmask_b32_e32 v106, v104, v102, vcc
	v_cndmask_b32_e32 v102, v102, v104, vcc
	ds_read_b128 v[76:79], v72 offset:17408
	ds_read_b128 v[80:83], v72 offset:17664
	ds_read_b128 v[84:87], v72 offset:17920
	ds_read_b128 v[88:91], v100 offset:48
	ds_read_b128 v[92:95], v72 offset:16896
	v_add_f32_dpp v102, v106, v102 quad_perm:[1,0,3,2] row_mask:0xf bank_mask:0xf bound_ctrl:1
	v_pk_fma_f32 v[96:97], v[66:67], v[0:1], v[2:3]
	v_cndmask_b32_e64 v106, v105, v102, s[4:5]
	v_cndmask_b32_e64 v102, v102, v105, s[4:5]
	ds_read_b128 v[0:3], v72 offset:18304
	v_add_f32_e32 v75, v96, v97
	s_waitcnt lgkmcnt(2)
; template <int CTRL> DI float dppf(float v) { return __int_as_float(__builtin_amdgcn_update_dpp(0, __float_as_int(v), CTRL, 0xf, 0xf, false)); }
; DI float red16(float p) { p += dppf<0xB1>(p); p += dppf<0x4E>(p); p += dppf<0x141>(p); p += dppf<0x140>(p); return p; }
; DI void scan_task(const Params& P, int sb, unsigned char* lds) {
;     ...
;         for (int i = 0; i < 4; ++i) {
;           ld_ops(nx3, gb + (i + 3) * SREC, q4);
;           const f2 a01 = {cur.a.x, cur.a.y}, a23 = {cur.a.z, cur.a.w}, w01 = {cur.w.x, cur.w.y}, w23 = {cur.w.z, cur.w.w};
;           const f2 k01 = {cur.k.x, cur.k.y}, k23 = {cur.k.z, cur.k.w}, b01 = {cur.b.x, cur.b.y}, b23 = {cur.b.z, cur.b.w};
;           const f2 r01 = {cur.r.x, cur.r.y}, r23 = {cur.r.z, cur.r.w};
;           f2 pa = S0 * a01; pa += S1 * a23;
;           const float vs = (i == 0) ? v4.x : (i == 1) ? v4.y : (i == 2) ? v4.z : v4.w;
;           const f2 vv = {vs, vs};
;           const f2 t0 = S0 * w01 + vv * k01, t1 = S1 * w23 + vv * k23;
;           const float sa = red16(pa.x + pa.y);
;           const f2 sa2 = {sa, sa};
;           S0 = t0 + sa2 * b01; S1 = t1 + sa2 * b23;
;           f2 py = S0 * r01; py += S1 * r23;
;           pp[i] = py.x + py.y;
;           cur = nxt; nxt = nx2; nx2 = nx3;
;         }
;         const float tA = o1 ? pp[0] : pp[1], kA = o1 ? pp[1] : pp[0];
;         const float tB = o1 ? pp[2] : pp[3], kB = o1 ? pp[3] : pp[2];
;         const float r0 = kA + dppf<0xB1>(tA), r1 = kB + dppf<0xB1>(tB);
;         const float tC = o2 ? r0 : r1, kC = o2 ? r1 : r0;
;         float u = kC + dppf<0x4E>(tC);
;         u += dppf<0x124>(u);
;         u += dppf<0x128>(u);
;         yb[(g4 * 4 + (q & 3)) * 16 + rowl] = u;
	v_add_f32_dpp v102, v106, v102 quad_perm:[2,3,0,1] row_mask:0xf bank_mask:0xf bound_ctrl:1
	v_pk_mul_f32 v[14:15], v[14:15], v[88:89] op_sel_hi:[1,0]
	v_pk_mul_f32 v[12:13], v[12:13], v[88:89] op_sel_hi:[1,0]
	v_add_f32_dpp v102, v102, v102 row_ror:4 row_mask:0xf bank_mask:0xf bound_ctrl:1
	v_add_f32_dpp v75, v75, v75 quad_perm:[1,0,3,2] row_mask:0xf bank_mask:0xf bound_ctrl:1
	v_pk_fma_f32 v[64:65], v[64:65], v[10:11], v[14:15]
	v_pk_fma_f32 v[66:67], v[66:67], v[8:9], v[12:13]
	v_add_f32_dpp v102, v102, v102 row_ror:8 row_mask:0xf bank_mask:0xf bound_ctrl:1
	v_add_f32_dpp v75, v75, v75 quad_perm:[2,3,0,1] row_mask:0xf bank_mask:0xf bound_ctrl:1
	v_mov_b32_e32 v98, v91
	ds_write_b32 v73, v102 offset:512
	v_add_f32_dpp v75, v75, v75 row_half_mirror row_mask:0xf bank_mask:0xf bound_ctrl:1
	ds_read_b128 v[8:11], v72 offset:18816
	ds_read_b128 v[12:15], v72 offset:19072
	v_add_f32_dpp v96, v75, v75 row_mirror row_mask:0xf bank_mask:0xf bound_ctrl:1
	v_pk_fma_f32 v[64:65], v[6:7], v[96:97], v[64:65] op_sel_hi:[1,0,1]
	v_pk_fma_f32 v[66:67], v[4:5], v[96:97], v[66:67] op_sel_hi:[1,0,1]
	v_pk_mul_f32 v[18:19], v[18:19], v[64:65]
	v_pk_mul_f32 v[22:23], v[22:23], v[64:65]
	v_pk_mul_f32 v[36:37], v[36:37], v[66:67]
	v_pk_mul_f32 v[38:39], v[38:39], v[64:65]
	v_pk_fma_f32 v[64:65], v[16:17], v[66:67], v[18:19]
	v_pk_fma_f32 v[66:67], v[20:21], v[66:67], v[22:23]
	v_add_f32_e32 v75, v64, v65
	v_add_f32_e32 v64, v66, v67
	v_pk_fma_f32 v[36:37], v[28:29], v[88:89], v[36:37] op_sel:[0,1,0]
	v_pk_fma_f32 v[38:39], v[30:31], v[88:89], v[38:39] op_sel:[0,1,0]
	v_add_f32_dpp v64, v64, v64 quad_perm:[1,0,3,2] row_mask:0xf bank_mask:0xf bound_ctrl:1
	ds_read_b128 v[4:7], v72 offset:18560
	ds_read_b128 v[16:19], v72 offset:19328
	v_add_f32_dpp v64, v64, v64 quad_perm:[2,3,0,1] row_mask:0xf bank_mask:0xf bound_ctrl:1
	ds_read_b128 v[20:23], v72 offset:19712
	ds_read_b128 v[28:31], v72 offset:20480
	v_add_f32_dpp v64, v64, v64 row_half_mirror row_mask:0xf bank_mask:0xf bound_ctrl:1
	s_nop 1
	v_add_f32_dpp v64, v64, v64 row_mirror row_mask:0xf bank_mask:0xf bound_ctrl:1
	v_pk_fma_f32 v[66:67], v[24:25], v[64:65], v[36:37] op_sel_hi:[1,0,1]
	v_pk_fma_f32 v[64:65], v[26:27], v[64:65], v[38:39] op_sel_hi:[1,0,1]
	v_pk_mul_f32 v[88:89], v[48:49], v[66:67]
	v_pk_mul_f32 v[34:35], v[34:35], v[64:65]
	v_pk_mul_f32 v[42:43], v[42:43], v[64:65]
	v_pk_fma_f32 v[96:97], v[32:33], v[66:67], v[34:35]
	v_pk_fma_f32 v[66:67], v[40:41], v[66:67], v[42:43]
	v_pk_mul_f32 v[64:65], v[50:51], v[64:65]
	v_add_f32_e32 v66, v66, v67
	v_pk_fma_f32 v[88:89], v[52:53], v[90:91], v[88:89] op_sel_hi:[1,0,1]
	v_pk_fma_f32 v[64:65], v[54:55], v[90:91], v[64:65] op_sel_hi:[1,0,1]
	v_add_f32_dpp v66, v66, v66 quad_perm:[1,0,3,2] row_mask:0xf bank_mask:0xf bound_ctrl:1
	v_add_f32_e32 v90, v96, v97
	v_cndmask_b32_e32 v67, v75, v90, vcc
	v_add_f32_dpp v66, v66, v66 quad_perm:[2,3,0,1] row_mask:0xf bank_mask:0xf bound_ctrl:1
	v_cndmask_b32_e32 v75, v90, v75, vcc
	ds_read_b128 v[24:27], v72 offset:19968
	ds_read_b128 v[36:39], v72 offset:20224
	v_add_f32_dpp v66, v66, v66 row_half_mirror row_mask:0xf bank_mask:0xf bound_ctrl:1
	v_add_f32_dpp v105, v67, v75 quad_perm:[1,0,3,2] row_mask:0xf bank_mask:0xf bound_ctrl:1
	ds_read_b128 v[48:51], v72 offset:21632
	ds_read_b128 v[32:35], v72 offset:20736
	v_add_f32_dpp v66, v66, v66 row_mirror row_mask:0xf bank_mask:0xf bound_ctrl:1
	v_pk_fma_f32 v[64:65], v[46:47], v[66:67], v[64:65] op_sel_hi:[1,0,1]
	v_pk_fma_f32 v[88:89], v[44:45], v[66:67], v[88:89] op_sel_hi:[1,0,1]
	s_waitcnt lgkmcnt(11)
	v_pk_mul_f32 v[66:67], v[94:95], v[64:65]
	v_pk_mul_f32 v[58:59], v[58:59], v[64:65]
	v_pk_fma_f32 v[66:67], v[92:93], v[88:89], v[66:67]
	v_pk_mul_f32 v[64:65], v[78:79], v[64:65]
	v_add_f32_e32 v66, v66, v67
	v_pk_fma_f32 v[78:79], v[56:57], v[88:89], v[58:59]
	v_pk_mul_f32 v[76:77], v[76:77], v[88:89]
	v_add_f32_dpp v66, v66, v66 quad_perm:[1,0,3,2] row_mask:0xf bank_mask:0xf bound_ctrl:1
	v_pk_fma_f32 v[64:65], v[98:99], v[82:83], v[64:65] op_sel_hi:[0,1,1]
	v_add_f32_e32 v104, v78, v79
	v_add_f32_dpp v66, v66, v66 quad_perm:[2,3,0,1] row_mask:0xf bank_mask:0xf bound_ctrl:1
	v_pk_fma_f32 v[76:77], v[98:99], v[80:81], v[76:77] op_sel_hi:[0,1,1]
	ds_read_b128 v[40:43], v72 offset:21120
	ds_read_b128 v[52:55], v72 offset:21888
	v_add_f32_dpp v66, v66, v66 row_half_mirror row_mask:0xf bank_mask:0xf bound_ctrl:1
	ds_read_b128 v[44:47], v72 offset:21376
	ds_read_b128 v[56:59], v72 offset:22144
	v_add_f32_dpp v78, v66, v66 row_mirror row_mask:0xf bank_mask:0xf bound_ctrl:1
	v_pk_fma_f32 v[64:65], v[62:63], v[78:79], v[64:65] op_sel_hi:[1,0,1]
	v_pk_fma_f32 v[66:67], v[60:61], v[78:79], v[76:77] op_sel_hi:[1,0,1]
	v_pk_mul_f32 v[102:103], v[86:87], v[64:65]
	v_pk_fma_f32 v[102:103], v[84:85], v[66:67], v[102:103]
	s_waitcnt lgkmcnt(14)
	v_pk_mul_f32 v[2:3], v[64:65], v[2:3]
	v_add_f32_e32 v102, v102, v103
	ds_read_b128 v[60:63], v72 offset:22784
	v_cndmask_b32_e32 v106, v104, v102, vcc
	v_cndmask_b32_e32 v102, v102, v104, vcc
	ds_read_b128 v[76:79], v72 offset:23040
	ds_read_b128 v[80:83], v72 offset:23296
	ds_read_b128 v[84:87], v72 offset:23552
	ds_read_b128 v[88:91], v100 offset:64
	ds_read_b128 v[92:95], v72 offset:22528
	v_add_f32_dpp v102, v106, v102 quad_perm:[1,0,3,2] row_mask:0xf bank_mask:0xf bound_ctrl:1
	v_pk_fma_f32 v[96:97], v[66:67], v[0:1], v[2:3]
	v_cndmask_b32_e64 v106, v105, v102, s[4:5]
	v_cndmask_b32_e64 v102, v102, v105, s[4:5]
	ds_read_b128 v[0:3], v72 offset:23936
	v_add_f32_e32 v75, v96, v97
	s_waitcnt lgkmcnt(2)
; template <int CTRL> DI float dppf(float v) { return __int_as_float(__builtin_amdgcn_update_dpp(0, __float_as_int(v), CTRL, 0xf, 0xf, false)); }
; DI float red16(float p) { p += dppf<0xB1>(p); p += dppf<0x4E>(p); p += dppf<0x141>(p); p += dppf<0x140>(p); return p; }
; DI void scan_task(const Params& P, int sb, unsigned char* lds) {
;     ...
;         for (int i = 0; i < 4; ++i) {
;           ld_ops(nx3, gb + (i + 3) * SREC, q4);
;           const f2 a01 = {cur.a.x, cur.a.y}, a23 = {cur.a.z, cur.a.w}, w01 = {cur.w.x, cur.w.y}, w23 = {cur.w.z, cur.w.w};
;           const f2 k01 = {cur.k.x, cur.k.y}, k23 = {cur.k.z, cur.k.w}, b01 = {cur.b.x, cur.b.y}, b23 = {cur.b.z, cur.b.w};
;           const f2 r01 = {cur.r.x, cur.r.y}, r23 = {cur.r.z, cur.r.w};
;           f2 pa = S0 * a01; pa += S1 * a23;
;           const float vs = (i == 0) ? v4.x : (i == 1) ? v4.y : (i == 2) ? v4.z : v4.w;
;           const f2 vv = {vs, vs};
;           const f2 t0 = S0 * w01 + vv * k01, t1 = S1 * w23 + vv * k23;
;           const float sa = red16(pa.x + pa.y);
;           const f2 sa2 = {sa, sa};
;           S0 = t0 + sa2 * b01; S1 = t1 + sa2 * b23;
;           f2 py = S0 * r01; py += S1 * r23;
;           pp[i] = py.x + py.y;
;           cur = nxt; nxt = nx2; nx2 = nx3;
;         }
;         const float tA = o1 ? pp[0] : pp[1], kA = o1 ? pp[1] : pp[0];
;         const float tB = o1 ? pp[2] : pp[3], kB = o1 ? pp[3] : pp[2];
;         const float r0 = kA + dppf<0xB1>(tA), r1 = kB + dppf<0xB1>(tB);
;         const float tC = o2 ? r0 : r1, kC = o2 ? r1 : r0;
;         float u = kC + dppf<0x4E>(tC);
;         u += dppf<0x124>(u);
;         u += dppf<0x128>(u);
;         yb[(g4 * 4 + (q & 3)) * 16 + rowl] = u;
	v_add_f32_dpp v102, v106, v102 quad_perm:[2,3,0,1] row_mask:0xf bank_mask:0xf bound_ctrl:1
	v_pk_mul_f32 v[14:15], v[14:15], v[88:89] op_sel_hi:[1,0]
	v_pk_mul_f32 v[12:13], v[12:13], v[88:89] op_sel_hi:[1,0]
	v_add_f32_dpp v102, v102, v102 row_ror:4 row_mask:0xf bank_mask:0xf bound_ctrl:1
	v_add_f32_dpp v75, v75, v75 quad_perm:[1,0,3,2] row_mask:0xf bank_mask:0xf bound_ctrl:1
	v_pk_fma_f32 v[64:65], v[64:65], v[10:11], v[14:15]
	v_pk_fma_f32 v[66:67], v[66:67], v[8:9], v[12:13]
	v_add_f32_dpp v102, v102, v102 row_ror:8 row_mask:0xf bank_mask:0xf bound_ctrl:1
	v_add_f32_dpp v75, v75, v75 quad_perm:[2,3,0,1] row_mask:0xf bank_mask:0xf bound_ctrl:1
	v_mov_b32_e32 v98, v91
	ds_write_b32 v73, v102 offset:768
	v_add_f32_dpp v75, v75, v75 row_half_mirror row_mask:0xf bank_mask:0xf bound_ctrl:1
	ds_read_b128 v[8:11], v72 offset:24448
	ds_read_b128 v[12:15], v72 offset:24704
	v_add_f32_dpp v96, v75, v75 row_mirror row_mask:0xf bank_mask:0xf bound_ctrl:1
	v_pk_fma_f32 v[64:65], v[6:7], v[96:97], v[64:65] op_sel_hi:[1,0,1]
	v_pk_fma_f32 v[66:67], v[4:5], v[96:97], v[66:67] op_sel_hi:[1,0,1]
	v_pk_mul_f32 v[18:19], v[18:19], v[64:65]
	v_pk_mul_f32 v[22:23], v[22:23], v[64:65]
	v_pk_mul_f32 v[36:37], v[36:37], v[66:67]
	v_pk_mul_f32 v[38:39], v[38:39], v[64:65]
	v_pk_fma_f32 v[64:65], v[16:17], v[66:67], v[18:19]
	v_pk_fma_f32 v[66:67], v[20:21], v[66:67], v[22:23]
	v_add_f32_e32 v75, v64, v65
	v_add_f32_e32 v64, v66, v67
	v_pk_fma_f32 v[36:37], v[28:29], v[88:89], v[36:37] op_sel:[0,1,0]
	v_pk_fma_f32 v[38:39], v[30:31], v[88:89], v[38:39] op_sel:[0,1,0]
	v_add_f32_dpp v64, v64, v64 quad_perm:[1,0,3,2] row_mask:0xf bank_mask:0xf bound_ctrl:1
	ds_read_b128 v[4:7], v72 offset:24192
	ds_read_b128 v[16:19], v72 offset:24960
	v_add_f32_dpp v64, v64, v64 quad_perm:[2,3,0,1] row_mask:0xf bank_mask:0xf bound_ctrl:1
	ds_read_b128 v[20:23], v72 offset:25344
	ds_read_b128 v[28:31], v72 offset:26112
	v_add_f32_dpp v64, v64, v64 row_half_mirror row_mask:0xf bank_mask:0xf bound_ctrl:1
	s_nop 1
	v_add_f32_dpp v64, v64, v64 row_mirror row_mask:0xf bank_mask:0xf bound_ctrl:1
	v_pk_fma_f32 v[66:67], v[24:25], v[64:65], v[36:37] op_sel_hi:[1,0,1]
	v_pk_fma_f32 v[64:65], v[26:27], v[64:65], v[38:39] op_sel_hi:[1,0,1]
	v_pk_mul_f32 v[88:89], v[48:49], v[66:67]
	v_pk_mul_f32 v[34:35], v[34:35], v[64:65]
	v_pk_mul_f32 v[42:43], v[42:43], v[64:65]
	v_pk_fma_f32 v[96:97], v[32:33], v[66:67], v[34:35]
	v_pk_fma_f32 v[66:67], v[40:41], v[66:67], v[42:43]
	v_pk_mul_f32 v[64:65], v[50:51], v[64:65]
	v_add_f32_e32 v66, v66, v67
	v_pk_fma_f32 v[88:89], v[52:53], v[90:91], v[88:89] op_sel_hi:[1,0,1]
	v_pk_fma_f32 v[64:65], v[54:55], v[90:91], v[64:65] op_sel_hi:[1,0,1]
	v_add_f32_dpp v66, v66, v66 quad_perm:[1,0,3,2] row_mask:0xf bank_mask:0xf bound_ctrl:1
	v_add_f32_e32 v90, v96, v97
	v_cndmask_b32_e32 v67, v75, v90, vcc
	v_add_f32_dpp v66, v66, v66 quad_perm:[2,3,0,1] row_mask:0xf bank_mask:0xf bound_ctrl:1
	v_cndmask_b32_e32 v75, v90, v75, vcc
	ds_read_b128 v[24:27], v72 offset:25600
	ds_read_b128 v[36:39], v72 offset:25856
	v_add_f32_dpp v66, v66, v66 row_half_mirror row_mask:0xf bank_mask:0xf bound_ctrl:1
	v_add_f32_dpp v105, v67, v75 quad_perm:[1,0,3,2] row_mask:0xf bank_mask:0xf bound_ctrl:1
	ds_read_b128 v[48:51], v72 offset:27264
	ds_read_b128 v[32:35], v72 offset:26368
	v_add_f32_dpp v66, v66, v66 row_mirror row_mask:0xf bank_mask:0xf bound_ctrl:1
	v_pk_fma_f32 v[64:65], v[46:47], v[66:67], v[64:65] op_sel_hi:[1,0,1]
	v_pk_fma_f32 v[88:89], v[44:45], v[66:67], v[88:89] op_sel_hi:[1,0,1]
	s_waitcnt lgkmcnt(11)
	v_pk_mul_f32 v[66:67], v[94:95], v[64:65]
	v_pk_mul_f32 v[58:59], v[58:59], v[64:65]
	v_pk_fma_f32 v[66:67], v[92:93], v[88:89], v[66:67]
	v_pk_mul_f32 v[64:65], v[78:79], v[64:65]
	v_add_f32_e32 v66, v66, v67
	v_pk_fma_f32 v[78:79], v[56:57], v[88:89], v[58:59]
	v_pk_mul_f32 v[76:77], v[76:77], v[88:89]
	v_add_f32_dpp v66, v66, v66 quad_perm:[1,0,3,2] row_mask:0xf bank_mask:0xf bound_ctrl:1
	v_pk_fma_f32 v[64:65], v[98:99], v[82:83], v[64:65] op_sel_hi:[0,1,1]
	v_add_f32_e32 v104, v78, v79
	v_add_f32_dpp v66, v66, v66 quad_perm:[2,3,0,1] row_mask:0xf bank_mask:0xf bound_ctrl:1
	v_pk_fma_f32 v[76:77], v[98:99], v[80:81], v[76:77] op_sel_hi:[0,1,1]
	ds_read_b128 v[40:43], v72 offset:26752
	ds_read_b128 v[52:55], v72 offset:27520
	v_add_f32_dpp v66, v66, v66 row_half_mirror row_mask:0xf bank_mask:0xf bound_ctrl:1
	ds_read_b128 v[44:47], v72 offset:27008
	ds_read_b128 v[56:59], v72 offset:27776
	v_add_f32_dpp v78, v66, v66 row_mirror row_mask:0xf bank_mask:0xf bound_ctrl:1
	v_pk_fma_f32 v[64:65], v[62:63], v[78:79], v[64:65] op_sel_hi:[1,0,1]
	v_pk_fma_f32 v[66:67], v[60:61], v[78:79], v[76:77] op_sel_hi:[1,0,1]
	v_pk_mul_f32 v[102:103], v[86:87], v[64:65]
	v_pk_fma_f32 v[102:103], v[84:85], v[66:67], v[102:103]
	s_waitcnt lgkmcnt(14)
	v_pk_mul_f32 v[2:3], v[64:65], v[2:3]
	v_add_f32_e32 v102, v102, v103
	ds_read_b128 v[60:63], v72 offset:28416
	v_cndmask_b32_e32 v106, v104, v102, vcc
	v_cndmask_b32_e32 v102, v102, v104, vcc
	ds_read_b128 v[76:79], v72 offset:28672
	ds_read_b128 v[80:83], v72 offset:28928
	ds_read_b128 v[84:87], v72 offset:29184
	ds_read_b128 v[88:91], v100 offset:80
	ds_read_b128 v[92:95], v72 offset:28160
	v_add_f32_dpp v102, v106, v102 quad_perm:[1,0,3,2] row_mask:0xf bank_mask:0xf bound_ctrl:1
	v_pk_fma_f32 v[96:97], v[66:67], v[0:1], v[2:3]
	v_cndmask_b32_e64 v106, v105, v102, s[4:5]
	v_cndmask_b32_e64 v102, v102, v105, s[4:5]
	ds_read_b128 v[0:3], v72 offset:29568
	v_add_f32_e32 v75, v96, v97
	s_waitcnt lgkmcnt(2)
; template <int CTRL> DI float dppf(float v) { return __int_as_float(__builtin_amdgcn_update_dpp(0, __float_as_int(v), CTRL, 0xf, 0xf, false)); }
; DI float red16(float p) { p += dppf<0xB1>(p); p += dppf<0x4E>(p); p += dppf<0x141>(p); p += dppf<0x140>(p); return p; }
; DI void scan_task(const Params& P, int sb, unsigned char* lds) {
;     ...
;         for (int i = 0; i < 4; ++i) {
;           ld_ops(nx3, gb + (i + 3) * SREC, q4);
;           const f2 a01 = {cur.a.x, cur.a.y}, a23 = {cur.a.z, cur.a.w}, w01 = {cur.w.x, cur.w.y}, w23 = {cur.w.z, cur.w.w};
;           const f2 k01 = {cur.k.x, cur.k.y}, k23 = {cur.k.z, cur.k.w}, b01 = {cur.b.x, cur.b.y}, b23 = {cur.b.z, cur.b.w};
;           const f2 r01 = {cur.r.x, cur.r.y}, r23 = {cur.r.z, cur.r.w};
;           f2 pa = S0 * a01; pa += S1 * a23;
;           const float vs = (i == 0) ? v4.x : (i == 1) ? v4.y : (i == 2) ? v4.z : v4.w;
;           const f2 vv = {vs, vs};
;           const f2 t0 = S0 * w01 + vv * k01, t1 = S1 * w23 + vv * k23;
;           const float sa = red16(pa.x + pa.y);
;           const f2 sa2 = {sa, sa};
;           S0 = t0 + sa2 * b01; S1 = t1 + sa2 * b23;
;           f2 py = S0 * r01; py += S1 * r23;
;           pp[i] = py.x + py.y;
;           cur = nxt; nxt = nx2; nx2 = nx3;
;         }
;         const float tA = o1 ? pp[0] : pp[1], kA = o1 ? pp[1] : pp[0];
;         const float tB = o1 ? pp[2] : pp[3], kB = o1 ? pp[3] : pp[2];
;         const float r0 = kA + dppf<0xB1>(tA), r1 = kB + dppf<0xB1>(tB);
;         const float tC = o2 ? r0 : r1, kC = o2 ? r1 : r0;
;         float u = kC + dppf<0x4E>(tC);
;         u += dppf<0x124>(u);
;         u += dppf<0x128>(u);
;         yb[(g4 * 4 + (q & 3)) * 16 + rowl] = u;
	v_add_f32_dpp v102, v106, v102 quad_perm:[2,3,0,1] row_mask:0xf bank_mask:0xf bound_ctrl:1
	v_pk_mul_f32 v[14:15], v[14:15], v[88:89] op_sel_hi:[1,0]
	v_pk_mul_f32 v[12:13], v[12:13], v[88:89] op_sel_hi:[1,0]
	v_add_f32_dpp v102, v102, v102 row_ror:4 row_mask:0xf bank_mask:0xf bound_ctrl:1
	v_add_f32_dpp v75, v75, v75 quad_perm:[1,0,3,2] row_mask:0xf bank_mask:0xf bound_ctrl:1
	v_pk_fma_f32 v[64:65], v[64:65], v[10:11], v[14:15]
	v_pk_fma_f32 v[66:67], v[66:67], v[8:9], v[12:13]
	v_add_f32_dpp v102, v102, v102 row_ror:8 row_mask:0xf bank_mask:0xf bound_ctrl:1
	v_add_f32_dpp v75, v75, v75 quad_perm:[2,3,0,1] row_mask:0xf bank_mask:0xf bound_ctrl:1
	v_mov_b32_e32 v98, v91
	ds_write_b32 v73, v102 offset:1024
	v_add_f32_dpp v75, v75, v75 row_half_mirror row_mask:0xf bank_mask:0xf bound_ctrl:1
	ds_read_b128 v[8:11], v72 offset:30080
	ds_read_b128 v[12:15], v72 offset:30336
	v_add_f32_dpp v96, v75, v75 row_mirror row_mask:0xf bank_mask:0xf bound_ctrl:1
	v_pk_fma_f32 v[64:65], v[6:7], v[96:97], v[64:65] op_sel_hi:[1,0,1]
	v_pk_fma_f32 v[66:67], v[4:5], v[96:97], v[66:67] op_sel_hi:[1,0,1]
	v_pk_mul_f32 v[18:19], v[18:19], v[64:65]
	v_pk_mul_f32 v[22:23], v[22:23], v[64:65]
	v_pk_mul_f32 v[36:37], v[36:37], v[66:67]
	v_pk_mul_f32 v[38:39], v[38:39], v[64:65]
	v_pk_fma_f32 v[64:65], v[16:17], v[66:67], v[18:19]
	v_pk_fma_f32 v[66:67], v[20:21], v[66:67], v[22:23]
	v_add_f32_e32 v75, v64, v65
	v_add_f32_e32 v64, v66, v67
	v_pk_fma_f32 v[36:37], v[28:29], v[88:89], v[36:37] op_sel:[0,1,0]
	v_pk_fma_f32 v[38:39], v[30:31], v[88:89], v[38:39] op_sel:[0,1,0]
	v_add_f32_dpp v64, v64, v64 quad_perm:[1,0,3,2] row_mask:0xf bank_mask:0xf bound_ctrl:1
	ds_read_b128 v[4:7], v72 offset:29824
	ds_read_b128 v[16:19], v72 offset:30592
	v_add_f32_dpp v64, v64, v64 quad_perm:[2,3,0,1] row_mask:0xf bank_mask:0xf bound_ctrl:1
	ds_read_b128 v[20:23], v72 offset:30976
	ds_read_b128 v[28:31], v72 offset:31744
	v_add_f32_dpp v64, v64, v64 row_half_mirror row_mask:0xf bank_mask:0xf bound_ctrl:1
	s_nop 1
	v_add_f32_dpp v64, v64, v64 row_mirror row_mask:0xf bank_mask:0xf bound_ctrl:1
	v_pk_fma_f32 v[66:67], v[24:25], v[64:65], v[36:37] op_sel_hi:[1,0,1]
	v_pk_fma_f32 v[64:65], v[26:27], v[64:65], v[38:39] op_sel_hi:[1,0,1]
	v_pk_mul_f32 v[88:89], v[48:49], v[66:67]
	v_pk_mul_f32 v[34:35], v[34:35], v[64:65]
	v_pk_mul_f32 v[42:43], v[42:43], v[64:65]
	v_pk_fma_f32 v[96:97], v[32:33], v[66:67], v[34:35]
	v_pk_fma_f32 v[66:67], v[40:41], v[66:67], v[42:43]
	v_pk_mul_f32 v[64:65], v[50:51], v[64:65]
	v_add_f32_e32 v66, v66, v67
	v_pk_fma_f32 v[88:89], v[52:53], v[90:91], v[88:89] op_sel_hi:[1,0,1]
	v_pk_fma_f32 v[64:65], v[54:55], v[90:91], v[64:65] op_sel_hi:[1,0,1]
	v_add_f32_dpp v66, v66, v66 quad_perm:[1,0,3,2] row_mask:0xf bank_mask:0xf bound_ctrl:1
	v_add_f32_e32 v90, v96, v97
	v_cndmask_b32_e32 v67, v75, v90, vcc
	v_add_f32_dpp v66, v66, v66 quad_perm:[2,3,0,1] row_mask:0xf bank_mask:0xf bound_ctrl:1
	v_cndmask_b32_e32 v75, v90, v75, vcc
	ds_read_b128 v[24:27], v72 offset:31232
	ds_read_b128 v[36:39], v72 offset:31488
	v_add_f32_dpp v66, v66, v66 row_half_mirror row_mask:0xf bank_mask:0xf bound_ctrl:1
	v_add_f32_dpp v105, v67, v75 quad_perm:[1,0,3,2] row_mask:0xf bank_mask:0xf bound_ctrl:1
	ds_read_b128 v[48:51], v72 offset:32896
	ds_read_b128 v[32:35], v72 offset:32000
	v_add_f32_dpp v66, v66, v66 row_mirror row_mask:0xf bank_mask:0xf bound_ctrl:1
	v_pk_fma_f32 v[64:65], v[46:47], v[66:67], v[64:65] op_sel_hi:[1,0,1]
	v_pk_fma_f32 v[88:89], v[44:45], v[66:67], v[88:89] op_sel_hi:[1,0,1]
	s_waitcnt lgkmcnt(11)
	v_pk_mul_f32 v[66:67], v[94:95], v[64:65]
	v_pk_mul_f32 v[58:59], v[58:59], v[64:65]
	v_pk_fma_f32 v[66:67], v[92:93], v[88:89], v[66:67]
	v_pk_mul_f32 v[64:65], v[78:79], v[64:65]
	v_add_f32_e32 v66, v66, v67
	v_pk_fma_f32 v[78:79], v[56:57], v[88:89], v[58:59]
	v_pk_mul_f32 v[76:77], v[76:77], v[88:89]
	v_add_f32_dpp v66, v66, v66 quad_perm:[1,0,3,2] row_mask:0xf bank_mask:0xf bound_ctrl:1
	v_pk_fma_f32 v[64:65], v[98:99], v[82:83], v[64:65] op_sel_hi:[0,1,1]
	v_add_f32_e32 v104, v78, v79
	v_add_f32_dpp v66, v66, v66 quad_perm:[2,3,0,1] row_mask:0xf bank_mask:0xf bound_ctrl:1
	v_pk_fma_f32 v[76:77], v[98:99], v[80:81], v[76:77] op_sel_hi:[0,1,1]
	ds_read_b128 v[40:43], v72 offset:32384
	ds_read_b128 v[52:55], v72 offset:33152
	v_add_f32_dpp v66, v66, v66 row_half_mirror row_mask:0xf bank_mask:0xf bound_ctrl:1
	ds_read_b128 v[44:47], v72 offset:32640
	ds_read_b128 v[56:59], v72 offset:33408
	v_add_f32_dpp v78, v66, v66 row_mirror row_mask:0xf bank_mask:0xf bound_ctrl:1
	v_pk_fma_f32 v[64:65], v[62:63], v[78:79], v[64:65] op_sel_hi:[1,0,1]
	v_pk_fma_f32 v[66:67], v[60:61], v[78:79], v[76:77] op_sel_hi:[1,0,1]
	v_pk_mul_f32 v[102:103], v[86:87], v[64:65]
	v_pk_fma_f32 v[102:103], v[84:85], v[66:67], v[102:103]
	s_waitcnt lgkmcnt(14)
	v_pk_mul_f32 v[2:3], v[64:65], v[2:3]
	v_add_f32_e32 v102, v102, v103
	ds_read_b128 v[60:63], v72 offset:34048
	v_cndmask_b32_e32 v106, v104, v102, vcc
	v_cndmask_b32_e32 v102, v102, v104, vcc
	ds_read_b128 v[76:79], v72 offset:34304
	ds_read_b128 v[80:83], v72 offset:34560
	ds_read_b128 v[84:87], v72 offset:34816
	ds_read_b128 v[88:91], v100 offset:96
	ds_read_b128 v[92:95], v72 offset:33792
	v_add_f32_dpp v102, v106, v102 quad_perm:[1,0,3,2] row_mask:0xf bank_mask:0xf bound_ctrl:1
	v_pk_fma_f32 v[96:97], v[66:67], v[0:1], v[2:3]
	v_cndmask_b32_e64 v106, v105, v102, s[4:5]
	v_cndmask_b32_e64 v102, v102, v105, s[4:5]
	ds_read_b128 v[0:3], v72 offset:35200
	v_add_f32_e32 v75, v96, v97
	s_waitcnt lgkmcnt(2)
; template <int CTRL> DI float dppf(float v) { return __int_as_float(__builtin_amdgcn_update_dpp(0, __float_as_int(v), CTRL, 0xf, 0xf, false)); }
; DI float red16(float p) { p += dppf<0xB1>(p); p += dppf<0x4E>(p); p += dppf<0x141>(p); p += dppf<0x140>(p); return p; }
; DI void scan_task(const Params& P, int sb, unsigned char* lds) {
;     ...
;         for (int i = 0; i < 4; ++i) {
;           ld_ops(nx3, gb + (i + 3) * SREC, q4);
;           const f2 a01 = {cur.a.x, cur.a.y}, a23 = {cur.a.z, cur.a.w}, w01 = {cur.w.x, cur.w.y}, w23 = {cur.w.z, cur.w.w};
;           const f2 k01 = {cur.k.x, cur.k.y}, k23 = {cur.k.z, cur.k.w}, b01 = {cur.b.x, cur.b.y}, b23 = {cur.b.z, cur.b.w};
;           const f2 r01 = {cur.r.x, cur.r.y}, r23 = {cur.r.z, cur.r.w};
;           f2 pa = S0 * a01; pa += S1 * a23;
;           const float vs = (i == 0) ? v4.x : (i == 1) ? v4.y : (i == 2) ? v4.z : v4.w;
;           const f2 vv = {vs, vs};
;           const f2 t0 = S0 * w01 + vv * k01, t1 = S1 * w23 + vv * k23;
;           const float sa = red16(pa.x + pa.y);
;           const f2 sa2 = {sa, sa};
;           S0 = t0 + sa2 * b01; S1 = t1 + sa2 * b23;
;           f2 py = S0 * r01; py += S1 * r23;
;           pp[i] = py.x + py.y;
;           cur = nxt; nxt = nx2; nx2 = nx3;
;         }
;         const float tA = o1 ? pp[0] : pp[1], kA = o1 ? pp[1] : pp[0];
;         const float tB = o1 ? pp[2] : pp[3], kB = o1 ? pp[3] : pp[2];
;         const float r0 = kA + dppf<0xB1>(tA), r1 = kB + dppf<0xB1>(tB);
;         const float tC = o2 ? r0 : r1, kC = o2 ? r1 : r0;
;         float u = kC + dppf<0x4E>(tC);
;         u += dppf<0x124>(u);
;         u += dppf<0x128>(u);
;         yb[(g4 * 4 + (q & 3)) * 16 + rowl] = u;
	v_add_f32_dpp v102, v106, v102 quad_perm:[2,3,0,1] row_mask:0xf bank_mask:0xf bound_ctrl:1
	v_pk_mul_f32 v[14:15], v[14:15], v[88:89] op_sel_hi:[1,0]
	v_pk_mul_f32 v[12:13], v[12:13], v[88:89] op_sel_hi:[1,0]
	v_add_f32_dpp v102, v102, v102 row_ror:4 row_mask:0xf bank_mask:0xf bound_ctrl:1
	v_add_f32_dpp v75, v75, v75 quad_perm:[1,0,3,2] row_mask:0xf bank_mask:0xf bound_ctrl:1
	v_pk_fma_f32 v[64:65], v[64:65], v[10:11], v[14:15]
	v_pk_fma_f32 v[66:67], v[66:67], v[8:9], v[12:13]
	v_add_f32_dpp v102, v102, v102 row_ror:8 row_mask:0xf bank_mask:0xf bound_ctrl:1
	v_add_f32_dpp v75, v75, v75 quad_perm:[2,3,0,1] row_mask:0xf bank_mask:0xf bound_ctrl:1
	v_mov_b32_e32 v98, v91
	ds_write_b32 v73, v102 offset:1280
	v_add_f32_dpp v75, v75, v75 row_half_mirror row_mask:0xf bank_mask:0xf bound_ctrl:1
	ds_read_b128 v[8:11], v72 offset:35712
	ds_read_b128 v[12:15], v72 offset:35968
	v_add_f32_dpp v96, v75, v75 row_mirror row_mask:0xf bank_mask:0xf bound_ctrl:1
	v_pk_fma_f32 v[64:65], v[6:7], v[96:97], v[64:65] op_sel_hi:[1,0,1]
	v_pk_fma_f32 v[66:67], v[4:5], v[96:97], v[66:67] op_sel_hi:[1,0,1]
	v_pk_mul_f32 v[18:19], v[18:19], v[64:65]
	v_pk_mul_f32 v[22:23], v[22:23], v[64:65]
	v_pk_mul_f32 v[36:37], v[36:37], v[66:67]
	v_pk_mul_f32 v[38:39], v[38:39], v[64:65]
	v_pk_fma_f32 v[64:65], v[16:17], v[66:67], v[18:19]
	v_pk_fma_f32 v[66:67], v[20:21], v[66:67], v[22:23]
	v_add_f32_e32 v75, v64, v65
	v_add_f32_e32 v64, v66, v67
	v_pk_fma_f32 v[36:37], v[28:29], v[88:89], v[36:37] op_sel:[0,1,0]
	v_pk_fma_f32 v[38:39], v[30:31], v[88:89], v[38:39] op_sel:[0,1,0]
	v_add_f32_dpp v64, v64, v64 quad_perm:[1,0,3,2] row_mask:0xf bank_mask:0xf bound_ctrl:1
	ds_read_b128 v[4:7], v72 offset:35456
	ds_read_b128 v[16:19], v72 offset:36224
	v_add_f32_dpp v64, v64, v64 quad_perm:[2,3,0,1] row_mask:0xf bank_mask:0xf bound_ctrl:1
	ds_read_b128 v[20:23], v72 offset:36608
	ds_read_b128 v[28:31], v72 offset:37376
	v_add_f32_dpp v64, v64, v64 row_half_mirror row_mask:0xf bank_mask:0xf bound_ctrl:1
	s_nop 1
	v_add_f32_dpp v64, v64, v64 row_mirror row_mask:0xf bank_mask:0xf bound_ctrl:1
	v_pk_fma_f32 v[66:67], v[24:25], v[64:65], v[36:37] op_sel_hi:[1,0,1]
	v_pk_fma_f32 v[64:65], v[26:27], v[64:65], v[38:39] op_sel_hi:[1,0,1]
	v_pk_mul_f32 v[88:89], v[48:49], v[66:67]
	v_pk_mul_f32 v[34:35], v[34:35], v[64:65]
	v_pk_mul_f32 v[42:43], v[42:43], v[64:65]
	v_pk_fma_f32 v[96:97], v[32:33], v[66:67], v[34:35]
	v_pk_fma_f32 v[66:67], v[40:41], v[66:67], v[42:43]
	v_pk_mul_f32 v[64:65], v[50:51], v[64:65]
	v_add_f32_e32 v66, v66, v67
	v_pk_fma_f32 v[88:89], v[52:53], v[90:91], v[88:89] op_sel_hi:[1,0,1]
	v_pk_fma_f32 v[64:65], v[54:55], v[90:91], v[64:65] op_sel_hi:[1,0,1]
	v_add_f32_dpp v66, v66, v66 quad_perm:[1,0,3,2] row_mask:0xf bank_mask:0xf bound_ctrl:1
	v_add_f32_e32 v90, v96, v97
	v_cndmask_b32_e32 v67, v75, v90, vcc
	v_add_f32_dpp v66, v66, v66 quad_perm:[2,3,0,1] row_mask:0xf bank_mask:0xf bound_ctrl:1
	v_cndmask_b32_e32 v75, v90, v75, vcc
	ds_read_b128 v[24:27], v72 offset:36864
	ds_read_b128 v[36:39], v72 offset:37120
	v_add_f32_dpp v66, v66, v66 row_half_mirror row_mask:0xf bank_mask:0xf bound_ctrl:1
	v_add_f32_dpp v105, v67, v75 quad_perm:[1,0,3,2] row_mask:0xf bank_mask:0xf bound_ctrl:1
	ds_read_b128 v[48:51], v72 offset:38528
	ds_read_b128 v[32:35], v72 offset:37632
	v_add_f32_dpp v66, v66, v66 row_mirror row_mask:0xf bank_mask:0xf bound_ctrl:1
	v_pk_fma_f32 v[64:65], v[46:47], v[66:67], v[64:65] op_sel_hi:[1,0,1]
	v_pk_fma_f32 v[88:89], v[44:45], v[66:67], v[88:89] op_sel_hi:[1,0,1]
	s_waitcnt lgkmcnt(11)
	v_pk_mul_f32 v[66:67], v[94:95], v[64:65]
	v_pk_mul_f32 v[58:59], v[58:59], v[64:65]
	v_pk_fma_f32 v[66:67], v[92:93], v[88:89], v[66:67]
	v_pk_mul_f32 v[64:65], v[78:79], v[64:65]
	v_add_f32_e32 v66, v66, v67
	v_pk_fma_f32 v[78:79], v[56:57], v[88:89], v[58:59]
	v_pk_mul_f32 v[76:77], v[76:77], v[88:89]
	v_add_f32_dpp v66, v66, v66 quad_perm:[1,0,3,2] row_mask:0xf bank_mask:0xf bound_ctrl:1
	v_pk_fma_f32 v[64:65], v[98:99], v[82:83], v[64:65] op_sel_hi:[0,1,1]
	v_add_f32_e32 v104, v78, v79
	v_add_f32_dpp v66, v66, v66 quad_perm:[2,3,0,1] row_mask:0xf bank_mask:0xf bound_ctrl:1
	v_pk_fma_f32 v[76:77], v[98:99], v[80:81], v[76:77] op_sel_hi:[0,1,1]
	ds_read_b128 v[40:43], v72 offset:38016
	ds_read_b128 v[52:55], v72 offset:38784
	v_add_f32_dpp v66, v66, v66 row_half_mirror row_mask:0xf bank_mask:0xf bound_ctrl:1
	ds_read_b128 v[44:47], v72 offset:38272
	ds_read_b128 v[56:59], v72 offset:39040
	v_add_f32_dpp v78, v66, v66 row_mirror row_mask:0xf bank_mask:0xf bound_ctrl:1
	v_pk_fma_f32 v[64:65], v[62:63], v[78:79], v[64:65] op_sel_hi:[1,0,1]
	v_pk_fma_f32 v[66:67], v[60:61], v[78:79], v[76:77] op_sel_hi:[1,0,1]
	v_pk_mul_f32 v[102:103], v[86:87], v[64:65]
	v_pk_fma_f32 v[102:103], v[84:85], v[66:67], v[102:103]
	s_waitcnt lgkmcnt(14)
	v_pk_mul_f32 v[2:3], v[64:65], v[2:3]
	v_add_f32_e32 v102, v102, v103
	ds_read_b128 v[60:63], v72 offset:39680
	v_cndmask_b32_e32 v106, v104, v102, vcc
	v_cndmask_b32_e32 v102, v102, v104, vcc
	ds_read_b128 v[76:79], v72 offset:39936
	ds_read_b128 v[80:83], v72 offset:40192
	ds_read_b128 v[84:87], v72 offset:40448
	ds_read_b128 v[88:91], v100 offset:112
	ds_read_b128 v[92:95], v72 offset:39424
	v_add_f32_dpp v102, v106, v102 quad_perm:[1,0,3,2] row_mask:0xf bank_mask:0xf bound_ctrl:1
	v_pk_fma_f32 v[96:97], v[66:67], v[0:1], v[2:3]
	v_cndmask_b32_e64 v106, v105, v102, s[4:5]
	v_cndmask_b32_e64 v102, v102, v105, s[4:5]
	ds_read_b128 v[0:3], v72 offset:40832
	v_add_f32_e32 v75, v96, v97
	s_waitcnt lgkmcnt(2)
; template <int CTRL> DI float dppf(float v) { return __int_as_float(__builtin_amdgcn_update_dpp(0, __float_as_int(v), CTRL, 0xf, 0xf, false)); }
; DI float red16(float p) { p += dppf<0xB1>(p); p += dppf<0x4E>(p); p += dppf<0x141>(p); p += dppf<0x140>(p); return p; }
; DI void scan_task(const Params& P, int sb, unsigned char* lds) {
;     ...
;         for (int i = 0; i < 4; ++i) {
;           ld_ops(nx3, gb + (i + 3) * SREC, q4);
;           const f2 a01 = {cur.a.x, cur.a.y}, a23 = {cur.a.z, cur.a.w}, w01 = {cur.w.x, cur.w.y}, w23 = {cur.w.z, cur.w.w};
;           const f2 k01 = {cur.k.x, cur.k.y}, k23 = {cur.k.z, cur.k.w}, b01 = {cur.b.x, cur.b.y}, b23 = {cur.b.z, cur.b.w};
;           const f2 r01 = {cur.r.x, cur.r.y}, r23 = {cur.r.z, cur.r.w};
;           f2 pa = S0 * a01; pa += S1 * a23;
;           const float vs = (i == 0) ? v4.x : (i == 1) ? v4.y : (i == 2) ? v4.z : v4.w;
;           const f2 vv = {vs, vs};
;           const f2 t0 = S0 * w01 + vv * k01, t1 = S1 * w23 + vv * k23;
;           const float sa = red16(pa.x + pa.y);
;           const f2 sa2 = {sa, sa};
;           S0 = t0 + sa2 * b01; S1 = t1 + sa2 * b23;
;           f2 py = S0 * r01; py += S1 * r23;
;           pp[i] = py.x + py.y;
;           cur = nxt; nxt = nx2; nx2 = nx3;
;         }
;         const float tA = o1 ? pp[0] : pp[1], kA = o1 ? pp[1] : pp[0];
;         const float tB = o1 ? pp[2] : pp[3], kB = o1 ? pp[3] : pp[2];
;         const float r0 = kA + dppf<0xB1>(tA), r1 = kB + dppf<0xB1>(tB);
;         const float tC = o2 ? r0 : r1, kC = o2 ? r1 : r0;
;         float u = kC + dppf<0x4E>(tC);
;         u += dppf<0x124>(u);
;         u += dppf<0x128>(u);
;         yb[(g4 * 4 + (q & 3)) * 16 + rowl] = u;
;       }
;       __syncthreads();
	v_add_f32_dpp v102, v106, v102 quad_perm:[2,3,0,1] row_mask:0xf bank_mask:0xf bound_ctrl:1
	v_pk_mul_f32 v[14:15], v[14:15], v[88:89] op_sel_hi:[1,0]
	v_pk_mul_f32 v[12:13], v[12:13], v[88:89] op_sel_hi:[1,0]
	v_add_f32_dpp v102, v102, v102 row_ror:4 row_mask:0xf bank_mask:0xf bound_ctrl:1
	v_add_f32_dpp v75, v75, v75 quad_perm:[1,0,3,2] row_mask:0xf bank_mask:0xf bound_ctrl:1
	v_pk_fma_f32 v[64:65], v[64:65], v[10:11], v[14:15]
	v_pk_fma_f32 v[66:67], v[66:67], v[8:9], v[12:13]
	v_add_f32_dpp v102, v102, v102 row_ror:8 row_mask:0xf bank_mask:0xf bound_ctrl:1
	v_add_f32_dpp v75, v75, v75 quad_perm:[2,3,0,1] row_mask:0xf bank_mask:0xf bound_ctrl:1
	v_mov_b32_e32 v98, v91
	ds_write_b32 v73, v102 offset:1536
	v_add_f32_dpp v75, v75, v75 row_half_mirror row_mask:0xf bank_mask:0xf bound_ctrl:1
	ds_read_b128 v[8:11], v72 offset:41344
	ds_read_b128 v[12:15], v72 offset:41600
	v_add_f32_dpp v96, v75, v75 row_mirror row_mask:0xf bank_mask:0xf bound_ctrl:1
	v_pk_fma_f32 v[64:65], v[6:7], v[96:97], v[64:65] op_sel_hi:[1,0,1]
	v_pk_fma_f32 v[66:67], v[4:5], v[96:97], v[66:67] op_sel_hi:[1,0,1]
	v_pk_mul_f32 v[18:19], v[18:19], v[64:65]
	v_pk_mul_f32 v[22:23], v[22:23], v[64:65]
	v_pk_mul_f32 v[36:37], v[36:37], v[66:67]
	v_pk_mul_f32 v[38:39], v[38:39], v[64:65]
	v_pk_fma_f32 v[64:65], v[16:17], v[66:67], v[18:19]
	v_pk_fma_f32 v[66:67], v[20:21], v[66:67], v[22:23]
	v_add_f32_e32 v75, v64, v65
	v_add_f32_e32 v64, v66, v67
	v_pk_fma_f32 v[36:37], v[28:29], v[88:89], v[36:37] op_sel:[0,1,0]
	v_pk_fma_f32 v[38:39], v[30:31], v[88:89], v[38:39] op_sel:[0,1,0]
	v_add_f32_dpp v64, v64, v64 quad_perm:[1,0,3,2] row_mask:0xf bank_mask:0xf bound_ctrl:1
	ds_read_b128 v[4:7], v72 offset:41088
	ds_read_b128 v[16:19], v72 offset:41856
	v_add_f32_dpp v64, v64, v64 quad_perm:[2,3,0,1] row_mask:0xf bank_mask:0xf bound_ctrl:1
	ds_read_b128 v[20:23], v72 offset:42240
	ds_read_b128 v[28:31], v72 offset:43008
	v_add_f32_dpp v64, v64, v64 row_half_mirror row_mask:0xf bank_mask:0xf bound_ctrl:1
	s_nop 1
	v_add_f32_dpp v64, v64, v64 row_mirror row_mask:0xf bank_mask:0xf bound_ctrl:1
	v_pk_fma_f32 v[66:67], v[24:25], v[64:65], v[36:37] op_sel_hi:[1,0,1]
	v_pk_fma_f32 v[64:65], v[26:27], v[64:65], v[38:39] op_sel_hi:[1,0,1]
	v_pk_mul_f32 v[88:89], v[48:49], v[66:67]
	v_pk_mul_f32 v[34:35], v[34:35], v[64:65]
	v_pk_mul_f32 v[42:43], v[42:43], v[64:65]
	v_pk_fma_f32 v[96:97], v[32:33], v[66:67], v[34:35]
	v_pk_fma_f32 v[66:67], v[40:41], v[66:67], v[42:43]
	v_pk_mul_f32 v[64:65], v[50:51], v[64:65]
	v_add_f32_e32 v66, v66, v67
	v_pk_fma_f32 v[88:89], v[52:53], v[90:91], v[88:89] op_sel_hi:[1,0,1]
	v_pk_fma_f32 v[64:65], v[54:55], v[90:91], v[64:65] op_sel_hi:[1,0,1]
	v_add_f32_dpp v66, v66, v66 quad_perm:[1,0,3,2] row_mask:0xf bank_mask:0xf bound_ctrl:1
	v_add_f32_e32 v90, v96, v97
	v_cndmask_b32_e32 v67, v75, v90, vcc
	v_add_f32_dpp v66, v66, v66 quad_perm:[2,3,0,1] row_mask:0xf bank_mask:0xf bound_ctrl:1
	v_cndmask_b32_e32 v75, v90, v75, vcc
	ds_read_b128 v[24:27], v72 offset:42496
	ds_read_b128 v[36:39], v72 offset:42752
	v_add_f32_dpp v66, v66, v66 row_half_mirror row_mask:0xf bank_mask:0xf bound_ctrl:1
	v_add_f32_dpp v105, v67, v75 quad_perm:[1,0,3,2] row_mask:0xf bank_mask:0xf bound_ctrl:1
	ds_read_b128 v[48:51], v72 offset:44160
	ds_read_b128 v[32:35], v72 offset:43264
	v_add_f32_dpp v66, v66, v66 row_mirror row_mask:0xf bank_mask:0xf bound_ctrl:1
	v_pk_fma_f32 v[64:65], v[46:47], v[66:67], v[64:65] op_sel_hi:[1,0,1]
	v_pk_fma_f32 v[88:89], v[44:45], v[66:67], v[88:89] op_sel_hi:[1,0,1]
	s_waitcnt lgkmcnt(11)
	v_pk_mul_f32 v[66:67], v[94:95], v[64:65]
	v_pk_mul_f32 v[58:59], v[58:59], v[64:65]
	v_pk_fma_f32 v[66:67], v[92:93], v[88:89], v[66:67]
	v_pk_mul_f32 v[64:65], v[78:79], v[64:65]
	v_add_f32_e32 v66, v66, v67
	v_pk_fma_f32 v[78:79], v[56:57], v[88:89], v[58:59]
	v_pk_mul_f32 v[76:77], v[76:77], v[88:89]
	v_add_f32_dpp v66, v66, v66 quad_perm:[1,0,3,2] row_mask:0xf bank_mask:0xf bound_ctrl:1
	v_pk_fma_f32 v[64:65], v[98:99], v[82:83], v[64:65] op_sel_hi:[0,1,1]
	v_add_f32_e32 v104, v78, v79
	v_add_f32_dpp v66, v66, v66 quad_perm:[2,3,0,1] row_mask:0xf bank_mask:0xf bound_ctrl:1
	v_pk_fma_f32 v[76:77], v[98:99], v[80:81], v[76:77] op_sel_hi:[0,1,1]
	ds_read_b128 v[40:43], v72 offset:43648
	ds_read_b128 v[52:55], v72 offset:44416
	v_add_f32_dpp v66, v66, v66 row_half_mirror row_mask:0xf bank_mask:0xf bound_ctrl:1
	ds_read_b128 v[44:47], v72 offset:43904
	ds_read_b128 v[56:59], v72 offset:44672
	v_add_f32_dpp v78, v66, v66 row_mirror row_mask:0xf bank_mask:0xf bound_ctrl:1
	v_pk_fma_f32 v[64:65], v[62:63], v[78:79], v[64:65] op_sel_hi:[1,0,1]
	v_pk_fma_f32 v[66:67], v[60:61], v[78:79], v[76:77] op_sel_hi:[1,0,1]
	v_pk_mul_f32 v[102:103], v[86:87], v[64:65]
	v_pk_fma_f32 v[102:103], v[84:85], v[66:67], v[102:103]
	s_nop 0
	v_add_f32_e32 v102, v102, v103
	v_cndmask_b32_e32 v106, v104, v102, vcc
	v_cndmask_b32_e32 v102, v102, v104, vcc
	s_nop 1
	v_add_f32_dpp v102, v106, v102 quad_perm:[1,0,3,2] row_mask:0xf bank_mask:0xf bound_ctrl:1
	v_cndmask_b32_e64 v106, v105, v102, s[4:5]
	v_cndmask_b32_e64 v102, v102, v105, s[4:5]
	s_nop 1
	v_add_f32_dpp v102, v106, v102 quad_perm:[2,3,0,1] row_mask:0xf bank_mask:0xf bound_ctrl:1
	s_nop 1
	v_add_f32_dpp v102, v102, v102 row_ror:4 row_mask:0xf bank_mask:0xf bound_ctrl:1
	s_nop 1
	v_add_f32_dpp v102, v102, v102 row_ror:8 row_mask:0xf bank_mask:0xf bound_ctrl:1
	ds_write_b32 v73, v102 offset:1792
	s_add_i32 s0, s0, 1
	s_xor_b64 s[6:7], s[6:7], -1
	s_cmpk_eq_i32 s0, 0x108
	s_waitcnt lgkmcnt(0)
	s_barrier
	s_cbranch_scc0 .LBB0_1197
	s_mov_b64 s[4:5], 0

; #define QKSTEP(off, qa, qbb) do { const bf16x8 a0 = *(const bf16x8*)(kp + (off)), a1 = *(const bf16x8*)(kp + 32 * AK_LD + (off)); \
;       s00 = MF(a0, qa, s00); s01 = MF(a1, qa, s01); s10 = MF(a0, qbb, s10); s11 = MF(a1, qbb, s11); } while (0)
; DI void attn_item(const Params& P, int item, unsigned char* lds) {
;     ...
;     QKSTEP(0, qa0, qb0); QKSTEP(16, qa1, qb1); QKSTEP(32, qa2, qb2); QKSTEP(48, qa3, qb3); QKSTEP(64, qa4, qb4); QKSTEP(80, qa5, qb5);
;     ...
;     SOFTMAX(s00, s01, m0, l0, O00, O01);
;     SOFTMAX(s10, s11, m1, l1, O10, O11);
.LBB0_1253:
	s_or_b64 exec, exec, s[24:25]
	s_and_b32 s24, s26, 1
	s_mul_i32 s25, s24, 0x3400
	v_add_u32_e32 v72, s25, v219
	ds_read_b128 v[64:67], v72
	ds_read_b128 v[68:71], v72 offset:32
	v_lshl_add_u64 v[236:237], s[94:95], 0, v[204:205]
	s_waitcnt lgkmcnt(1)
	v_mfma_f32_32x32x16_bf16 v[112:127], v[64:67], v[176:179], 0
	v_mfma_f32_32x32x16_bf16 v[96:111], v[64:67], v[152:155], 0
	s_waitcnt lgkmcnt(0)
	v_mfma_f32_32x32x16_bf16 v[112:127], v[68:71], v[172:175], v[112:127]
	v_mfma_f32_32x32x16_bf16 v[96:111], v[68:71], v[148:151], v[96:111]
	ds_read_b128 v[64:67], v72 offset:64
	ds_read_b128 v[68:71], v72 offset:96
	s_waitcnt lgkmcnt(1)
	v_mfma_f32_32x32x16_bf16 v[112:127], v[64:67], v[168:171], v[112:127]
	v_mfma_f32_32x32x16_bf16 v[96:111], v[64:67], v[144:147], v[96:111]
	s_waitcnt lgkmcnt(0)
	v_mfma_f32_32x32x16_bf16 v[112:127], v[68:71], v[164:167], v[112:127]
	v_mfma_f32_32x32x16_bf16 v[96:111], v[68:71], v[140:143], v[96:111]
	ds_read_b128 v[64:67], v72 offset:128
	ds_read_b128 v[68:71], v72 offset:160
	s_waitcnt lgkmcnt(1)
	v_mfma_f32_32x32x16_bf16 v[112:127], v[64:67], v[160:163], v[112:127]
	v_mfma_f32_32x32x16_bf16 v[96:111], v[64:67], v[136:139], v[96:111]
	ds_read_b128 v[64:67], v72 offset:6656
	ds_read_b128 v[184:187], v72 offset:6688
	ds_read_b128 v[220:223], v72 offset:6720
	ds_read_b128 v[224:227], v72 offset:6752
	ds_read_b128 v[228:231], v72 offset:6784
	ds_read_b128 v[232:235], v72 offset:6816
	s_waitcnt lgkmcnt(6)
	v_mfma_f32_32x32x16_bf16 v[112:127], v[68:71], v[156:159], v[112:127]
	v_mfma_f32_32x32x16_bf16 v[112:127], v[244:247], v[248:251], v[112:127]
	v_mfma_f32_32x32x16_bf16 v[96:111], v[68:71], v[132:135], v[96:111]
	v_mfma_f32_32x32x16_bf16 v[96:111], v[244:247], v[252:255], v[96:111]
	s_waitcnt lgkmcnt(5)
	v_mfma_f32_32x32x16_bf16 v[80:95], v[64:67], v[176:179], 0
	v_mfma_f32_32x32x16_bf16 v[64:79], v[64:67], v[152:155], 0
	s_waitcnt lgkmcnt(4)
	v_mfma_f32_32x32x16_bf16 v[80:95], v[184:187], v[172:175], v[80:95]
	v_mfma_f32_32x32x16_bf16 v[64:79], v[184:187], v[148:151], v[64:79]
	global_load_dwordx4 v[184:187], v[236:237], off
	s_nop 3
	v_max_f32_e32 v236, v113, v113
	v_max_f32_e32 v237, v112, v112
	v_max_f32_e32 v236, v237, v236
	v_max3_f32 v236, v236, v114, v115
	s_waitcnt lgkmcnt(3)
	v_mfma_f32_32x32x16_bf16 v[80:95], v[220:223], v[168:171], v[80:95]
	s_waitcnt lgkmcnt(2)
	v_mfma_f32_32x32x16_bf16 v[80:95], v[224:227], v[164:167], v[80:95]
	v_mfma_f32_32x32x16_bf16 v[64:79], v[220:223], v[144:147], v[64:79]
	v_max3_f32 v220, v236, v116, v117
	v_max3_f32 v220, v220, v118, v119
	v_max3_f32 v220, v220, v120, v121
	v_max3_f32 v220, v220, v122, v123
	v_max3_f32 v220, v220, v124, v125
	v_max3_f32 v220, v220, v126, v127
	s_waitcnt lgkmcnt(1)
	v_mfma_f32_32x32x16_bf16 v[80:95], v[228:231], v[160:163], v[80:95]
	v_mfma_f32_32x32x16_bf16 v[64:79], v[224:227], v[140:143], v[64:79]
	s_waitcnt lgkmcnt(0)
	v_mfma_f32_32x32x16_bf16 v[80:95], v[232:235], v[156:159], v[80:95]
	v_mfma_f32_32x32x16_bf16 v[80:95], v[244:247], v[248:251], v[80:95]
	v_mfma_f32_32x32x16_bf16 v[64:79], v[228:231], v[136:139], v[64:79]
	v_max3_f32 v236, v96, v97, v98
	v_max3_f32 v237, v99, v100, v101
	v_mfma_f32_32x32x16_bf16 v[64:79], v[232:235], v[132:135], v[64:79]
	v_mfma_f32_32x32x16_bf16 v[64:79], v[244:247], v[252:255], v[64:79]
	v_max3_f32 v236, v236, v102, v103
	v_max3_f32 v237, v237, v104, v105
	v_max3_f32 v236, v236, v106, v107
	v_max3_f32 v237, v237, v108, v109
	v_max3_f32 v236, v236, v110, v111
	v_max_f32_e32 v236, v236, v237
	s_nop 0
	v_max3_f32 v220, v220, v80, v81
	v_max3_f32 v223, v82, v83, v84
	v_max3_f32 v220, v220, v85, v86
	v_max3_f32 v223, v223, v87, v88
	v_max3_f32 v220, v220, v89, v90
	v_max3_f32 v223, v223, v91, v92
	v_max3_f32 v220, v220, v93, v94
	v_max3_f32 v220, v220, v223, v95
	v_mov_b32_e32 v223, v220
	v_max3_f32 v236, v236, v64, v65
	v_max3_f32 v237, v66, v67, v68
	v_permlane32_swap_b32_e32 v220, v223
	v_max3_f32 v236, v236, v69, v70
	v_max3_f32 v237, v237, v71, v72
	v_max_f32_e32 v220, v220, v223
	v_max3_f32 v236, v236, v73, v74
	v_max3_f32 v237, v237, v75, v76
	v_max3_f32 v236, v236, v77, v78
	v_max3_f32 v236, v236, v237, v79
	s_cmp_eq_u32 s26, 0
	s_cbranch_scc1 .Lcf_rare_a
	v_cmp_lt_f32_e32 vcc, 0, v220
	s_cbranch_vccz .LBB0_1255

.LBB0_1255:
	v_mov_b32_e32 v237, v236
	s_nop 1
	v_permlane32_swap_b32_e32 v236, v237
	v_max_f32_e32 v220, v236, v237
	s_cmp_eq_u32 s26, 0
	s_cbranch_scc1 .Lcf_rare_b
	v_cmp_lt_f32_e32 vcc, 0, v220
	s_cbranch_vccz .LBB0_1257
